# MLA: one static s_setprio 1 for the early wave half during the MLA units
# speedup vs baseline: 1.0056x; 1.0053x over previous
.LBB0_1174:
	v_readfirstlane_b32 s64, v206
	s_nop 3
	s_lshr_b32 s64, s64, 8
	s_mov_b32 s66, 0
	s_mov_b32 s67, 0x8000
	s_cmp_eq_u32 s64, 0
	s_cbranch_scc0 .Lmla_prio_skip
	s_setprio 1
